# P9 rwkv_post row loop unrolled by two and rotated: next trip's loads requested before the current trip's arithmetic (on top of v020)
# speedup vs baseline: 1.0021x; 1.0021x over previous
; __device__ __forceinline__ void rwkv_post(const P& p, Frame& F) {
;     ...
;     for (int it = gw; it < MT * 4; it += NGW) { const int m = it >> 2, h = 4 * (it & 3) + q, c0 = h * 64 + 4 * c;
;         size_t sr; if (m < MP) sr = (size_t)((m >> 11) * RWH + h) * TP + (m & (TP - 1)); else { const int x = m - MP; sr = (size_t)NSEQ_P * TP + (size_t)((x >> 2) * RWH + h) * TS + (x & 3); }
.LBB0_2455:
	v_mov_b32_e32 v51, 0
	s_ashr_i32 s8, s4, 2
	v_and_or_b32 v13, s11, 12, v1
	s_cmpk_gt_i32 s8, 0x3fff
	s_mov_b64 s[0:1], -1
	s_cbranch_scc0 .Lp9_a0_57
	s_add_i32 s0, s4, 0x7fff0000
	s_and_b32 s0, s0, 0x7ffffff0
	v_or_b32_e32 v2, s0, v13
	v_lshl_add_u64 v[8:9], v[2:3], 2, v[6:7]
	s_mov_b64 s[0:1], 0

; __device__ __forceinline__ f32x4 bf4(const u32x2 w) { return (f32x4){bflo(w.x), bfhi(w.x), bflo(w.y), bfhi(w.y)}; }
; __device__ __forceinline__ void rwkv_post(const P& p, Frame& F) {
;     ...
;     for (int it = gw; it < MT * 4; it += NGW) { const int m = it >> 2, h = 4 * (it & 3) + q, c0 = h * 64 + 4 * c;
;         size_t sr; if (m < MP) sr = (size_t)((m >> 11) * RWH + h) * TP + (m & (TP - 1)); else { const int x = m - MP; sr = (size_t)NSEQ_P * TP + (size_t)((x >> 2) * RWH + h) * TS + (x & 3); }
;         const f32x4 y = bf4(*(const u32x2*)(YRAW + (size_t)m * 1024 + c0)), vv = bf4(*(const u32x2*)(VVB + sr * 64 + 4 * c)), g = bf4(*(const u32x2*)(GG + (size_t)m * 1024 + c0));
.Lp9_a0_54:
	s_and_b32 s6, s0, s8
	s_ashr_i32 s9, s8, 31
	v_lshl_add_u64 v[8:9], v[8:9], 0, s[6:7]
	s_lshl_b64 s[0:1], s[8:9], 11
	v_lshl_or_b32 v14, v13, 6, v10
	v_lshlrev_b64 v[8:9], 7, v[8:9]
	s_add_u32 s14, s5, s0
	v_lshl_add_u64 v[8:9], v[4:5], 0, v[8:9]
	s_addc_u32 s15, s10, s1
	v_lshlrev_b32_e32 v36, 1, v14
	global_load_dwordx2 v[8:9], v[8:9], off
	v_readlane_b32 s16, v254, 31
	global_load_dwordx2 v[22:23], v36, s[14:15]
	v_readlane_b32 s14, v252, 3
	v_readlane_b32 s15, v252, 4
	s_add_u32 s14, s14, s0
	s_addc_u32 s15, s15, s1
	s_lshl_b64 s[8:9], s[8:9], 6
	s_add_u32 s8, s64, s8
	v_lshlrev_b32_e32 v2, 2, v13
	s_addc_u32 s9, s65, s9
	v_lshlrev_b32_e32 v13, 2, v14
	v_readlane_b32 s17, v254, 32
	global_load_dword v2, v2, s[8:9]
	s_nop 0
	global_load_dwordx2 v[24:25], v36, s[14:15]
	v_readlane_b32 s18, v254, 33
	v_readlane_b32 s19, v254, 34
	global_load_dwordx4 v[14:17], v13, s[16:17]
	s_nop 3
	global_load_dwordx4 v[18:21], v13, s[18:19]
	s_add_u32 s98, s2, s0
	s_addc_u32 s99, s3, s1
	s_add_i32 s4, s4, s50
	s_add_i32 s11, s11, s12
	s_cmp_lt_i32 s4, 0x10200
	v_readlane_b32 s20, v254, 35
	v_readlane_b32 s21, v254, 36
	v_readlane_b32 s22, v254, 37
	v_readlane_b32 s23, v254, 38
	v_readlane_b32 s24, v254, 39
	v_readlane_b32 s25, v254, 40
	v_readlane_b32 s26, v254, 41
	v_readlane_b32 s27, v254, 42
	v_readlane_b32 s28, v254, 43
	v_readlane_b32 s29, v254, 44
	v_readlane_b32 s30, v254, 45
	v_readlane_b32 s31, v254, 46
.Lp9_loop:
	s_cmp_lt_i32 s4, 0x10200
	s_cbranch_scc0 .Lp9_lastA
	s_ashr_i32 s8, s4, 2
	v_and_or_b32 v61, s11, 12, v1
	s_cmpk_gt_i32 s8, 0x3fff
	s_mov_b64 s[0:1], -1
	s_cbranch_scc0 .Lp9_b_57
	s_add_i32 s0, s4, 0x7fff0000
	s_and_b32 s0, s0, 0x7ffffff0
	v_or_b32_e32 v50, s0, v61
	v_lshl_add_u64 v[56:57], v[50:51], 2, v[6:7]
	s_mov_b64 s[0:1], 0
.Lp9_b_57:
	s_andn2_b64 vcc, exec, s[0:1]
	s_mov_b32 s0, 3
	s_cbranch_vccnz .Lp9_b_54
	s_ashr_i32 s0, s4, 9
	v_and_or_b32 v56, s0, -16, v61
	v_ashrrev_i32_e32 v57, 31, v56
	v_lshlrev_b64 v[56:57], 11, v[56:57]
	s_movk_i32 s0, 0x7ff
; __device__ __forceinline__ unsigned pk2(float lo, float hi) { const bfx2 b = __builtin_convertvector((f32x2){lo, hi}, bfx2); return __builtin_bit_cast(unsigned, b); }
; __device__ __forceinline__ f32x4 bf4(const u32x2 w) { return (f32x4){bflo(w.x), bfhi(w.x), bflo(w.y), bfhi(w.y)}; }
; __device__ __forceinline__ void rwkv_post(const P& p, Frame& F) {
;     ...
;         size_t sr; if (m < MP) sr = (size_t)((m >> 11) * RWH + h) * TP + (m & (TP - 1)); else { const int x = m - MP; sr = (size_t)NSEQ_P * TP + (size_t)((x >> 2) * RWH + h) * TS + (x & 3); }
;         const f32x4 y = bf4(*(const u32x2*)(YRAW + (size_t)m * 1024 + c0)), vv = bf4(*(const u32x2*)(VVB + sr * 64 + 4 * c)), g = bf4(*(const u32x2*)(GG + (size_t)m * 1024 + c0));
;         const float cb = CB[(size_t)m * 16 + h];
;         const float mean = red16((y.x + y.y) + (y.z + y.w)) * (1.0f / 64.0f); const f32x4 dd = y - mean;
;         const float var = red16((dd.x * dd.x + dd.y * dd.y) + (dd.z * dd.z + dd.w * dd.w)) * (1.0f / 64.0f);
;         const f32x4 yn = dd * (1.0f / sqrtf(var + RW_LN_EPS)) * *(const f32x4*)(p.in[I_LNW] + c0) + *(const f32x4*)(p.in[I_LNB] + c0);
;         const f32x4 o = (yn + vv * cb) * g;
;         u32x2 w; w.x = pk2(o.x, o.y); w.y = pk2(o.z, o.w); *(u32x2*)(YRW + (size_t)m * 1024 + c0) = w; }
.Lp9_b_54:
	s_and_b32 s6, s0, s8
	s_ashr_i32 s9, s8, 31
	v_lshl_add_u64 v[56:57], v[56:57], 0, s[6:7]
	s_lshl_b64 s[0:1], s[8:9], 11
	v_lshl_or_b32 v62, v61, 6, v10
	v_lshlrev_b64 v[56:57], 7, v[56:57]
	s_add_u32 s14, s5, s0
	v_lshl_add_u64 v[56:57], v[4:5], 0, v[56:57]
	s_addc_u32 s15, s10, s1
	v_lshlrev_b32_e32 v84, 1, v62
	global_load_dwordx2 v[56:57], v[56:57], off
	v_readlane_b32 s16, v254, 31
	global_load_dwordx2 v[70:71], v84, s[14:15]
	v_readlane_b32 s14, v252, 3
	v_readlane_b32 s15, v252, 4
	s_add_u32 s14, s14, s0
	s_addc_u32 s15, s15, s1
	s_lshl_b64 s[8:9], s[8:9], 6
	s_add_u32 s8, s64, s8
	v_lshlrev_b32_e32 v50, 2, v61
	s_addc_u32 s9, s65, s9
	v_lshlrev_b32_e32 v61, 2, v62
	v_readlane_b32 s17, v254, 32
	global_load_dword v50, v50, s[8:9]
	s_nop 0
	global_load_dwordx2 v[72:73], v84, s[14:15]
	v_readlane_b32 s18, v254, 33
	v_readlane_b32 s19, v254, 34
	global_load_dwordx4 v[62:65], v61, s[16:17]
	s_nop 3
	global_load_dwordx4 v[66:69], v61, s[18:19]
	s_add_u32 s100, s2, s0
	s_addc_u32 s101, s3, s1
	s_add_i32 s4, s4, s50
	s_add_i32 s11, s11, s12
	s_cmp_lt_i32 s4, 0x10200
	v_readlane_b32 s20, v254, 35
	v_readlane_b32 s21, v254, 36
	v_readlane_b32 s22, v254, 37
	v_readlane_b32 s23, v254, 38
	v_readlane_b32 s24, v254, 39
	v_readlane_b32 s25, v254, 40
	v_readlane_b32 s26, v254, 41
	v_readlane_b32 s27, v254, 42
	v_readlane_b32 s28, v254, 43
	v_readlane_b32 s29, v254, 44
	v_readlane_b32 s30, v254, 45
	v_readlane_b32 s31, v254, 46
	s_waitcnt vmcnt(11)
	v_lshlrev_b32_e32 v26, 16, v8
	v_and_b32_e32 v27, 0xffff0000, v8
	s_waitcnt vmcnt(10)
	v_lshlrev_b32_e32 v29, 16, v23
	v_lshlrev_b32_e32 v28, 16, v22
	v_and_b32_e32 v23, 0xffff0000, v23
	v_and_b32_e32 v22, 0xffff0000, v22
	v_pk_add_f32 v[30:31], v[28:29], v[22:23]
	v_lshlrev_b32_e32 v8, 16, v9
	v_add_f32_e32 v13, v30, v31
	v_and_b32_e32 v9, 0xffff0000, v9
	s_nop 0
	v_add_f32_dpp v13, v13, v13 quad_perm:[1,0,3,2] row_mask:0xf bank_mask:0xf bound_ctrl:1
	s_nop 1
	v_add_f32_dpp v13, v13, v13 quad_perm:[2,3,0,1] row_mask:0xf bank_mask:0xf bound_ctrl:1
	s_nop 1
	v_add_f32_dpp v13, v13, v13 row_half_mirror row_mask:0xf bank_mask:0xf bound_ctrl:1
	s_nop 1
	v_add_f32_dpp v13, v13, v13 row_mirror row_mask:0xf bank_mask:0xf bound_ctrl:1
	v_fmac_f32_e32 v22, 0xbc800000, v13
	v_fmac_f32_e32 v23, 0xbc800000, v13
	v_fmac_f32_e32 v29, 0xbc800000, v13
	v_fmac_f32_e32 v28, 0xbc800000, v13
	v_mov_b32_e32 v30, v29
	v_mov_b32_e32 v31, v23
	v_mov_b32_e32 v29, v22
	v_pk_mul_f32 v[22:23], v[30:31], v[30:31]
	v_pk_mul_f32 v[32:33], v[28:29], v[28:29]
	s_nop 0
	v_pk_mov_b32 v[34:35], v[32:33], v[22:23] op_sel:[1,0]
	v_mov_b32_e32 v33, v23
	v_pk_add_f32 v[22:23], v[34:35], v[32:33]
	s_nop 0
	v_add_f32_e32 v13, v22, v23
	s_waitcnt vmcnt(8)
	v_and_b32_e32 v23, 0xffff0000, v24
	v_add_f32_dpp v13, v13, v13 quad_perm:[1,0,3,2] row_mask:0xf bank_mask:0xf bound_ctrl:1
	s_nop 1
	v_add_f32_dpp v13, v13, v13 quad_perm:[2,3,0,1] row_mask:0xf bank_mask:0xf bound_ctrl:1
	s_nop 1
	v_add_f32_dpp v13, v13, v13 row_half_mirror row_mask:0xf bank_mask:0xf bound_ctrl:1
	s_nop 1
	v_add_f32_dpp v13, v13, v13 row_mirror row_mask:0xf bank_mask:0xf bound_ctrl:1
	v_fmamk_f32 v13, v13, 0x3c800000, v11
	v_mul_f32_e32 v22, 0x4f800000, v13
	v_cmp_gt_f32_e32 vcc, s13, v13
	s_nop 1
	v_cndmask_b32_e32 v13, v13, v22, vcc
	v_sqrt_f32_e32 v32, v13
	v_lshlrev_b32_e32 v22, 16, v24
	v_lshlrev_b32_e32 v24, 16, v25
	v_and_b32_e32 v25, 0xffff0000, v25
	v_add_u32_e32 v33, -1, v32
	v_add_u32_e32 v34, 1, v32
	v_fma_f32 v35, -v33, v32, v13
	v_fma_f32 v37, -v34, v32, v13
	v_cmp_ge_f32_e64 s[0:1], 0, v35
	s_nop 1
	v_cndmask_b32_e64 v32, v32, v33, s[0:1]
	v_cmp_lt_f32_e64 s[0:1], 0, v37
	s_nop 1
	v_cndmask_b32_e64 v32, v32, v34, s[0:1]
	v_mul_f32_e32 v33, 0x37800000, v32
	v_cndmask_b32_e32 v32, v32, v33, vcc
	v_cmp_class_f32_e32 vcc, v13, v12
	s_nop 1
	v_cndmask_b32_e32 v13, v32, v13, vcc
	v_div_scale_f32 v32, s[0:1], v13, v13, 1.0
	v_rcp_f32_e32 v33, v32
	v_div_scale_f32 v34, vcc, 1.0, v13, 1.0
	v_fma_f32 v35, -v32, v33, 1.0
	v_fmac_f32_e32 v33, v35, v33
	v_mul_f32_e32 v35, v34, v33
	v_fma_f32 v37, -v32, v35, v34
	v_fmac_f32_e32 v35, v37, v33
	v_fma_f32 v32, -v32, v35, v34
	v_div_fmas_f32 v32, v32, v33, v35
	v_div_fixup_f32 v32, v32, v13, 1.0
	v_pk_mul_f32 v[28:29], v[28:29], v[32:33] op_sel_hi:[1,0]
	v_pk_mul_f32 v[30:31], v[30:31], v[32:33] op_sel_hi:[1,0]
	s_waitcnt vmcnt(6)
	v_pk_fma_f32 v[14:15], v[14:15], v[28:29], v[18:19]
	v_pk_fma_f32 v[16:17], v[16:17], v[30:31], v[20:21]
	v_pk_fma_f32 v[14:15], v[2:3], v[26:27], v[14:15] op_sel_hi:[0,1,1]
	v_pk_fma_f32 v[8:9], v[2:3], v[8:9], v[16:17] op_sel_hi:[0,1,1]
	v_pk_mul_f32 v[8:9], v[8:9], v[24:25]
	v_pk_mul_f32 v[14:15], v[14:15], v[22:23]
	s_nop 0
	v_cvt_pk_bf16_f32 v14, v14, v15
	v_cvt_pk_bf16_f32 v15, v8, v9
	global_store_dwordx2 v36, v[14:15], s[98:99]
	s_cmp_lt_i32 s4, 0x10200
	s_cbranch_scc0 .Lp9_lastB
	s_ashr_i32 s8, s4, 2
	v_and_or_b32 v13, s11, 12, v1
	s_cmpk_gt_i32 s8, 0x3fff
	s_mov_b64 s[0:1], -1
	s_cbranch_scc0 .Lp9_a1_57
	s_add_i32 s0, s4, 0x7fff0000
	s_and_b32 s0, s0, 0x7ffffff0
	v_or_b32_e32 v2, s0, v13
	v_lshl_add_u64 v[8:9], v[2:3], 2, v[6:7]
	s_mov_b64 s[0:1], 0

; __device__ __forceinline__ unsigned pk2(float lo, float hi) { const bfx2 b = __builtin_convertvector((f32x2){lo, hi}, bfx2); return __builtin_bit_cast(unsigned, b); }
; __device__ __forceinline__ f32x4 bf4(const u32x2 w) { return (f32x4){bflo(w.x), bfhi(w.x), bflo(w.y), bfhi(w.y)}; }
; __device__ __forceinline__ void rwkv_post(const P& p, Frame& F) {
;     ...
;         size_t sr; if (m < MP) sr = (size_t)((m >> 11) * RWH + h) * TP + (m & (TP - 1)); else { const int x = m - MP; sr = (size_t)NSEQ_P * TP + (size_t)((x >> 2) * RWH + h) * TS + (x & 3); }
;         const f32x4 y = bf4(*(const u32x2*)(YRAW + (size_t)m * 1024 + c0)), vv = bf4(*(const u32x2*)(VVB + sr * 64 + 4 * c)), g = bf4(*(const u32x2*)(GG + (size_t)m * 1024 + c0));
;         const float cb = CB[(size_t)m * 16 + h];
;         const float mean = red16((y.x + y.y) + (y.z + y.w)) * (1.0f / 64.0f); const f32x4 dd = y - mean;
;         const float var = red16((dd.x * dd.x + dd.y * dd.y) + (dd.z * dd.z + dd.w * dd.w)) * (1.0f / 64.0f);
;         const f32x4 yn = dd * (1.0f / sqrtf(var + RW_LN_EPS)) * *(const f32x4*)(p.in[I_LNW] + c0) + *(const f32x4*)(p.in[I_LNB] + c0);
;         const f32x4 o = (yn + vv * cb) * g;
;         u32x2 w; w.x = pk2(o.x, o.y); w.y = pk2(o.z, o.w); *(u32x2*)(YRW + (size_t)m * 1024 + c0) = w; }
.Lp9_a1_54:
	s_and_b32 s6, s0, s8
	s_ashr_i32 s9, s8, 31
	v_lshl_add_u64 v[8:9], v[8:9], 0, s[6:7]
	s_lshl_b64 s[0:1], s[8:9], 11
	v_lshl_or_b32 v14, v13, 6, v10
	v_lshlrev_b64 v[8:9], 7, v[8:9]
	s_add_u32 s14, s5, s0
	v_lshl_add_u64 v[8:9], v[4:5], 0, v[8:9]
	s_addc_u32 s15, s10, s1
	v_lshlrev_b32_e32 v36, 1, v14
	global_load_dwordx2 v[8:9], v[8:9], off
	v_readlane_b32 s16, v254, 31
	global_load_dwordx2 v[22:23], v36, s[14:15]
	v_readlane_b32 s14, v252, 3
	v_readlane_b32 s15, v252, 4
	s_add_u32 s14, s14, s0
	s_addc_u32 s15, s15, s1
	s_lshl_b64 s[8:9], s[8:9], 6
	s_add_u32 s8, s64, s8
	v_lshlrev_b32_e32 v2, 2, v13
	s_addc_u32 s9, s65, s9
	v_lshlrev_b32_e32 v13, 2, v14
	v_readlane_b32 s17, v254, 32
	global_load_dword v2, v2, s[8:9]
	s_nop 0
	global_load_dwordx2 v[24:25], v36, s[14:15]
	v_readlane_b32 s18, v254, 33
	v_readlane_b32 s19, v254, 34
	global_load_dwordx4 v[14:17], v13, s[16:17]
	s_nop 3
	global_load_dwordx4 v[18:21], v13, s[18:19]
	s_add_u32 s98, s2, s0
	s_addc_u32 s99, s3, s1
	s_add_i32 s4, s4, s50
	s_add_i32 s11, s11, s12
	s_cmp_lt_i32 s4, 0x10200
	v_readlane_b32 s20, v254, 35
	v_readlane_b32 s21, v254, 36
	v_readlane_b32 s22, v254, 37
	v_readlane_b32 s23, v254, 38
	v_readlane_b32 s24, v254, 39
	v_readlane_b32 s25, v254, 40
	v_readlane_b32 s26, v254, 41
	v_readlane_b32 s27, v254, 42
	v_readlane_b32 s28, v254, 43
	v_readlane_b32 s29, v254, 44
	v_readlane_b32 s30, v254, 45
	v_readlane_b32 s31, v254, 46
	s_waitcnt vmcnt(11)
	v_lshlrev_b32_e32 v74, 16, v56
	v_and_b32_e32 v75, 0xffff0000, v56
	s_waitcnt vmcnt(10)
	v_lshlrev_b32_e32 v77, 16, v71
	v_lshlrev_b32_e32 v76, 16, v70
	v_and_b32_e32 v71, 0xffff0000, v71
	v_and_b32_e32 v70, 0xffff0000, v70
	v_pk_add_f32 v[78:79], v[76:77], v[70:71]
	v_lshlrev_b32_e32 v56, 16, v57
	v_add_f32_e32 v61, v78, v79
	v_and_b32_e32 v57, 0xffff0000, v57
	s_nop 0
	v_add_f32_dpp v61, v61, v61 quad_perm:[1,0,3,2] row_mask:0xf bank_mask:0xf bound_ctrl:1
	s_nop 1
	v_add_f32_dpp v61, v61, v61 quad_perm:[2,3,0,1] row_mask:0xf bank_mask:0xf bound_ctrl:1
	s_nop 1
	v_add_f32_dpp v61, v61, v61 row_half_mirror row_mask:0xf bank_mask:0xf bound_ctrl:1
	s_nop 1
	v_add_f32_dpp v61, v61, v61 row_mirror row_mask:0xf bank_mask:0xf bound_ctrl:1
	v_fmac_f32_e32 v70, 0xbc800000, v61
	v_fmac_f32_e32 v71, 0xbc800000, v61
	v_fmac_f32_e32 v77, 0xbc800000, v61
	v_fmac_f32_e32 v76, 0xbc800000, v61
	v_mov_b32_e32 v78, v77
	v_mov_b32_e32 v79, v71
	v_mov_b32_e32 v77, v70
	v_pk_mul_f32 v[70:71], v[78:79], v[78:79]
	v_pk_mul_f32 v[80:81], v[76:77], v[76:77]
	s_nop 0
	v_pk_mov_b32 v[82:83], v[80:81], v[70:71] op_sel:[1,0]
	v_mov_b32_e32 v81, v71
	v_pk_add_f32 v[70:71], v[82:83], v[80:81]
	s_nop 0
	v_add_f32_e32 v61, v70, v71
	s_waitcnt vmcnt(8)
	v_and_b32_e32 v71, 0xffff0000, v72
	v_add_f32_dpp v61, v61, v61 quad_perm:[1,0,3,2] row_mask:0xf bank_mask:0xf bound_ctrl:1
	s_nop 1
	v_add_f32_dpp v61, v61, v61 quad_perm:[2,3,0,1] row_mask:0xf bank_mask:0xf bound_ctrl:1
	s_nop 1
	v_add_f32_dpp v61, v61, v61 row_half_mirror row_mask:0xf bank_mask:0xf bound_ctrl:1
	s_nop 1
	v_add_f32_dpp v61, v61, v61 row_mirror row_mask:0xf bank_mask:0xf bound_ctrl:1
	v_fmamk_f32 v61, v61, 0x3c800000, v11
	v_mul_f32_e32 v70, 0x4f800000, v61
	v_cmp_gt_f32_e32 vcc, s13, v61
	s_nop 1
	v_cndmask_b32_e32 v61, v61, v70, vcc
	v_sqrt_f32_e32 v80, v61
	v_lshlrev_b32_e32 v70, 16, v72
	v_lshlrev_b32_e32 v72, 16, v73
	v_and_b32_e32 v73, 0xffff0000, v73
	v_add_u32_e32 v81, -1, v80
	v_add_u32_e32 v82, 1, v80
	v_fma_f32 v83, -v81, v80, v61
	v_fma_f32 v85, -v82, v80, v61
	v_cmp_ge_f32_e64 s[0:1], 0, v83
	s_nop 1
	v_cndmask_b32_e64 v80, v80, v81, s[0:1]
	v_cmp_lt_f32_e64 s[0:1], 0, v85
	s_nop 1
	v_cndmask_b32_e64 v80, v80, v82, s[0:1]
	v_mul_f32_e32 v81, 0x37800000, v80
	v_cndmask_b32_e32 v80, v80, v81, vcc
	v_cmp_class_f32_e32 vcc, v61, v12
	s_nop 1
	v_cndmask_b32_e32 v61, v80, v61, vcc
	v_div_scale_f32 v80, s[0:1], v61, v61, 1.0
	v_rcp_f32_e32 v81, v80
	v_div_scale_f32 v82, vcc, 1.0, v61, 1.0
	v_fma_f32 v83, -v80, v81, 1.0
	v_fmac_f32_e32 v81, v83, v81
	v_mul_f32_e32 v83, v82, v81
	v_fma_f32 v85, -v80, v83, v82
	v_fmac_f32_e32 v83, v85, v81
	v_fma_f32 v80, -v80, v83, v82
	v_div_fmas_f32 v80, v80, v81, v83
	v_div_fixup_f32 v80, v80, v61, 1.0
	v_pk_mul_f32 v[76:77], v[76:77], v[80:81] op_sel_hi:[1,0]
	v_pk_mul_f32 v[78:79], v[78:79], v[80:81] op_sel_hi:[1,0]
	s_waitcnt vmcnt(6)
	v_pk_fma_f32 v[62:63], v[62:63], v[76:77], v[66:67]
	v_pk_fma_f32 v[64:65], v[64:65], v[78:79], v[68:69]
	v_pk_fma_f32 v[62:63], v[50:51], v[74:75], v[62:63] op_sel_hi:[0,1,1]
	v_pk_fma_f32 v[56:57], v[50:51], v[56:57], v[64:65] op_sel_hi:[0,1,1]
	v_pk_mul_f32 v[56:57], v[56:57], v[72:73]
	v_pk_mul_f32 v[62:63], v[62:63], v[70:71]
	s_nop 0
	v_cvt_pk_bf16_f32 v62, v62, v63
	v_cvt_pk_bf16_f32 v63, v56, v57
	global_store_dwordx2 v84, v[62:63], s[100:101]
	s_branch .Lp9_loop
; __device__ __forceinline__ unsigned pk2(float lo, float hi) { const bfx2 b = __builtin_convertvector((f32x2){lo, hi}, bfx2); return __builtin_bit_cast(unsigned, b); }
; __device__ __forceinline__ f32x4 bf4(const u32x2 w) { return (f32x4){bflo(w.x), bfhi(w.x), bflo(w.y), bfhi(w.y)}; }
; __device__ __forceinline__ void rwkv_post(const P& p, Frame& F) {
;     ...
;         const f32x4 y = bf4(*(const u32x2*)(YRAW + (size_t)m * 1024 + c0)), vv = bf4(*(const u32x2*)(VVB + sr * 64 + 4 * c)), g = bf4(*(const u32x2*)(GG + (size_t)m * 1024 + c0));
;         const float cb = CB[(size_t)m * 16 + h];
;         const float mean = red16((y.x + y.y) + (y.z + y.w)) * (1.0f / 64.0f); const f32x4 dd = y - mean;
;         const float var = red16((dd.x * dd.x + dd.y * dd.y) + (dd.z * dd.z + dd.w * dd.w)) * (1.0f / 64.0f);
;         const f32x4 yn = dd * (1.0f / sqrtf(var + RW_LN_EPS)) * *(const f32x4*)(p.in[I_LNW] + c0) + *(const f32x4*)(p.in[I_LNB] + c0);
;         const f32x4 o = (yn + vv * cb) * g;
;         u32x2 w; w.x = pk2(o.x, o.y); w.y = pk2(o.z, o.w); *(u32x2*)(YRW + (size_t)m * 1024 + c0) = w; }
.Lp9_lastA:
	s_waitcnt vmcnt(5)
	v_lshlrev_b32_e32 v26, 16, v8
	v_and_b32_e32 v27, 0xffff0000, v8
	s_waitcnt vmcnt(4)
	v_lshlrev_b32_e32 v29, 16, v23
	v_lshlrev_b32_e32 v28, 16, v22
	v_and_b32_e32 v23, 0xffff0000, v23
	v_and_b32_e32 v22, 0xffff0000, v22
	v_pk_add_f32 v[30:31], v[28:29], v[22:23]
	v_lshlrev_b32_e32 v8, 16, v9
	v_add_f32_e32 v13, v30, v31
	v_and_b32_e32 v9, 0xffff0000, v9
	s_nop 0
	v_add_f32_dpp v13, v13, v13 quad_perm:[1,0,3,2] row_mask:0xf bank_mask:0xf bound_ctrl:1
	s_nop 1
	v_add_f32_dpp v13, v13, v13 quad_perm:[2,3,0,1] row_mask:0xf bank_mask:0xf bound_ctrl:1
	s_nop 1
	v_add_f32_dpp v13, v13, v13 row_half_mirror row_mask:0xf bank_mask:0xf bound_ctrl:1
	s_nop 1
	v_add_f32_dpp v13, v13, v13 row_mirror row_mask:0xf bank_mask:0xf bound_ctrl:1
	v_fmac_f32_e32 v22, 0xbc800000, v13
	v_fmac_f32_e32 v23, 0xbc800000, v13
	v_fmac_f32_e32 v29, 0xbc800000, v13
	v_fmac_f32_e32 v28, 0xbc800000, v13
	v_mov_b32_e32 v30, v29
	v_mov_b32_e32 v31, v23
	v_mov_b32_e32 v29, v22
	v_pk_mul_f32 v[22:23], v[30:31], v[30:31]
	v_pk_mul_f32 v[32:33], v[28:29], v[28:29]
	s_nop 0
	v_pk_mov_b32 v[34:35], v[32:33], v[22:23] op_sel:[1,0]
	v_mov_b32_e32 v33, v23
	v_pk_add_f32 v[22:23], v[34:35], v[32:33]
	s_nop 0
	v_add_f32_e32 v13, v22, v23
	s_waitcnt vmcnt(2)
	v_and_b32_e32 v23, 0xffff0000, v24
	v_add_f32_dpp v13, v13, v13 quad_perm:[1,0,3,2] row_mask:0xf bank_mask:0xf bound_ctrl:1
	s_nop 1
	v_add_f32_dpp v13, v13, v13 quad_perm:[2,3,0,1] row_mask:0xf bank_mask:0xf bound_ctrl:1
	s_nop 1
	v_add_f32_dpp v13, v13, v13 row_half_mirror row_mask:0xf bank_mask:0xf bound_ctrl:1
	s_nop 1
	v_add_f32_dpp v13, v13, v13 row_mirror row_mask:0xf bank_mask:0xf bound_ctrl:1
	v_fmamk_f32 v13, v13, 0x3c800000, v11
	v_mul_f32_e32 v22, 0x4f800000, v13
	v_cmp_gt_f32_e32 vcc, s13, v13
	s_nop 1
	v_cndmask_b32_e32 v13, v13, v22, vcc
	v_sqrt_f32_e32 v32, v13
	v_lshlrev_b32_e32 v22, 16, v24
	v_lshlrev_b32_e32 v24, 16, v25
	v_and_b32_e32 v25, 0xffff0000, v25
	v_add_u32_e32 v33, -1, v32
	v_add_u32_e32 v34, 1, v32
	v_fma_f32 v35, -v33, v32, v13
	v_fma_f32 v37, -v34, v32, v13
	v_cmp_ge_f32_e64 s[0:1], 0, v35
	s_nop 1
	v_cndmask_b32_e64 v32, v32, v33, s[0:1]
	v_cmp_lt_f32_e64 s[0:1], 0, v37
	s_nop 1
	v_cndmask_b32_e64 v32, v32, v34, s[0:1]
	v_mul_f32_e32 v33, 0x37800000, v32
	v_cndmask_b32_e32 v32, v32, v33, vcc
	v_cmp_class_f32_e32 vcc, v13, v12
	s_nop 1
	v_cndmask_b32_e32 v13, v32, v13, vcc
	v_div_scale_f32 v32, s[0:1], v13, v13, 1.0
	v_rcp_f32_e32 v33, v32
	v_div_scale_f32 v34, vcc, 1.0, v13, 1.0
	v_fma_f32 v35, -v32, v33, 1.0
	v_fmac_f32_e32 v33, v35, v33
	v_mul_f32_e32 v35, v34, v33
	v_fma_f32 v37, -v32, v35, v34
	v_fmac_f32_e32 v35, v37, v33
	v_fma_f32 v32, -v32, v35, v34
	v_div_fmas_f32 v32, v32, v33, v35
	v_div_fixup_f32 v32, v32, v13, 1.0
	v_pk_mul_f32 v[28:29], v[28:29], v[32:33] op_sel_hi:[1,0]
	v_pk_mul_f32 v[30:31], v[30:31], v[32:33] op_sel_hi:[1,0]
	s_waitcnt vmcnt(0)
	v_pk_fma_f32 v[14:15], v[14:15], v[28:29], v[18:19]
	v_pk_fma_f32 v[16:17], v[16:17], v[30:31], v[20:21]
	v_pk_fma_f32 v[14:15], v[2:3], v[26:27], v[14:15] op_sel_hi:[0,1,1]
	v_pk_fma_f32 v[8:9], v[2:3], v[8:9], v[16:17] op_sel_hi:[0,1,1]
	v_pk_mul_f32 v[8:9], v[8:9], v[24:25]
	v_pk_mul_f32 v[14:15], v[14:15], v[22:23]
	s_nop 0
	v_cvt_pk_bf16_f32 v14, v14, v15
	v_cvt_pk_bf16_f32 v15, v8, v9
	global_store_dwordx2 v36, v[14:15], s[98:99]
	s_branch .LBB0_2459
.Lp9_lastB:
	s_waitcnt vmcnt(5)
	v_lshlrev_b32_e32 v74, 16, v56
	v_and_b32_e32 v75, 0xffff0000, v56
	s_waitcnt vmcnt(4)
	v_lshlrev_b32_e32 v77, 16, v71
	v_lshlrev_b32_e32 v76, 16, v70
	v_and_b32_e32 v71, 0xffff0000, v71
	v_and_b32_e32 v70, 0xffff0000, v70
	v_pk_add_f32 v[78:79], v[76:77], v[70:71]
	v_lshlrev_b32_e32 v56, 16, v57
	v_add_f32_e32 v61, v78, v79
	v_and_b32_e32 v57, 0xffff0000, v57
	s_nop 0
	v_add_f32_dpp v61, v61, v61 quad_perm:[1,0,3,2] row_mask:0xf bank_mask:0xf bound_ctrl:1
	s_nop 1
	v_add_f32_dpp v61, v61, v61 quad_perm:[2,3,0,1] row_mask:0xf bank_mask:0xf bound_ctrl:1
	s_nop 1
	v_add_f32_dpp v61, v61, v61 row_half_mirror row_mask:0xf bank_mask:0xf bound_ctrl:1
	s_nop 1
	v_add_f32_dpp v61, v61, v61 row_mirror row_mask:0xf bank_mask:0xf bound_ctrl:1
	v_fmac_f32_e32 v70, 0xbc800000, v61
	v_fmac_f32_e32 v71, 0xbc800000, v61
	v_fmac_f32_e32 v77, 0xbc800000, v61
	v_fmac_f32_e32 v76, 0xbc800000, v61
	v_mov_b32_e32 v78, v77
	v_mov_b32_e32 v79, v71
	v_mov_b32_e32 v77, v70
	v_pk_mul_f32 v[70:71], v[78:79], v[78:79]
	v_pk_mul_f32 v[80:81], v[76:77], v[76:77]
	s_nop 0
	v_pk_mov_b32 v[82:83], v[80:81], v[70:71] op_sel:[1,0]
	v_mov_b32_e32 v81, v71
	v_pk_add_f32 v[70:71], v[82:83], v[80:81]
	s_nop 0
	v_add_f32_e32 v61, v70, v71
	s_waitcnt vmcnt(2)
	v_and_b32_e32 v71, 0xffff0000, v72
	v_add_f32_dpp v61, v61, v61 quad_perm:[1,0,3,2] row_mask:0xf bank_mask:0xf bound_ctrl:1
	s_nop 1
	v_add_f32_dpp v61, v61, v61 quad_perm:[2,3,0,1] row_mask:0xf bank_mask:0xf bound_ctrl:1
	s_nop 1
	v_add_f32_dpp v61, v61, v61 row_half_mirror row_mask:0xf bank_mask:0xf bound_ctrl:1
	s_nop 1
	v_add_f32_dpp v61, v61, v61 row_mirror row_mask:0xf bank_mask:0xf bound_ctrl:1
	v_fmamk_f32 v61, v61, 0x3c800000, v11
	v_mul_f32_e32 v70, 0x4f800000, v61
	v_cmp_gt_f32_e32 vcc, s13, v61
	s_nop 1
	v_cndmask_b32_e32 v61, v61, v70, vcc
	v_sqrt_f32_e32 v80, v61
	v_lshlrev_b32_e32 v70, 16, v72
	v_lshlrev_b32_e32 v72, 16, v73
	v_and_b32_e32 v73, 0xffff0000, v73
	v_add_u32_e32 v81, -1, v80
	v_add_u32_e32 v82, 1, v80
	v_fma_f32 v83, -v81, v80, v61
	v_fma_f32 v85, -v82, v80, v61
	v_cmp_ge_f32_e64 s[0:1], 0, v83
	s_nop 1
	v_cndmask_b32_e64 v80, v80, v81, s[0:1]
	v_cmp_lt_f32_e64 s[0:1], 0, v85
	s_nop 1
	v_cndmask_b32_e64 v80, v80, v82, s[0:1]
	v_mul_f32_e32 v81, 0x37800000, v80
	v_cndmask_b32_e32 v80, v80, v81, vcc
	v_cmp_class_f32_e32 vcc, v61, v12
	s_nop 1
	v_cndmask_b32_e32 v61, v80, v61, vcc
	v_div_scale_f32 v80, s[0:1], v61, v61, 1.0
	v_rcp_f32_e32 v81, v80
	v_div_scale_f32 v82, vcc, 1.0, v61, 1.0
	v_fma_f32 v83, -v80, v81, 1.0
	v_fmac_f32_e32 v81, v83, v81
	v_mul_f32_e32 v83, v82, v81
	v_fma_f32 v85, -v80, v83, v82
	v_fmac_f32_e32 v83, v85, v81
	v_fma_f32 v80, -v80, v83, v82
	v_div_fmas_f32 v80, v80, v81, v83
	v_div_fixup_f32 v80, v80, v61, 1.0
	v_pk_mul_f32 v[76:77], v[76:77], v[80:81] op_sel_hi:[1,0]
	v_pk_mul_f32 v[78:79], v[78:79], v[80:81] op_sel_hi:[1,0]
	s_waitcnt vmcnt(0)
	v_pk_fma_f32 v[62:63], v[62:63], v[76:77], v[66:67]
	v_pk_fma_f32 v[64:65], v[64:65], v[78:79], v[68:69]
	v_pk_fma_f32 v[62:63], v[50:51], v[74:75], v[62:63] op_sel_hi:[0,1,1]
	v_pk_fma_f32 v[56:57], v[50:51], v[56:57], v[64:65] op_sel_hi:[0,1,1]
	v_pk_mul_f32 v[56:57], v[56:57], v[72:73]
	v_pk_mul_f32 v[62:63], v[62:63], v[70:71]
	s_nop 0
	v_cvt_pk_bf16_f32 v62, v62, v63
	v_cvt_pk_bf16_f32 v63, v56, v57
	global_store_dwordx2 v84, v[62:63], s[100:101]
	s_branch .LBB0_2459
